# attention: 8 waves of a workgroup share K/V tiles through a 3-slot LDS ring filled by LDS-DMA (1 barrier per key row), task bits remapped so an XCD owns a head; epilogue gate loads batched
# speedup vs baseline: 1.0553x; 1.0380x over previous
.LBB0_280:
	ds_bpermute_b32 v50, v171, v201
	ds_bpermute_b32 v51, v171, v175
	v_or_b32_e32 v52, s13, v197
	v_lshlrev_b32_e32 v194, 1, v52
	v_lshl_add_u64 v[60:61], v[186:187], 0, s[20:21]
	v_lshl_add_u64 v[56:57], v[182:183], 0, s[20:21]
	v_lshl_add_u64 v[60:61], v[60:61], 0, v[194:195]
	v_lshl_add_u64 v[56:57], v[56:57], 0, v[194:195]
	global_load_dwordx2 v[98:99], v[60:61], off
	global_load_dwordx2 v[100:101], v[60:61], off offset:32
	global_load_dwordx2 v[102:103], v[60:61], off offset:64
	global_load_dwordx2 v[104:105], v[60:61], off offset:96
	global_load_dwordx2 v[106:107], v[60:61], off offset:128
	global_load_dwordx2 v[108:109], v[60:61], off offset:160
	global_load_dwordx2 v[110:111], v[60:61], off offset:192
	global_load_dwordx2 v[112:113], v[60:61], off offset:224
	global_load_dwordx2 v[114:115], v[56:57], off
	global_load_dwordx2 v[116:117], v[56:57], off offset:32
	global_load_dwordx2 v[118:119], v[56:57], off offset:64
	global_load_dwordx2 v[120:121], v[56:57], off offset:96
	global_load_dwordx2 v[122:123], v[56:57], off offset:128
	global_load_dwordx2 v[124:125], v[56:57], off offset:160
	global_load_dwordx2 v[126:127], v[56:57], off offset:192
	global_load_dwordx2 v[128:129], v[56:57], off offset:224
	v_ashrrev_i32_e32 v185, 31, v184
	v_ashrrev_i32_e32 v181, 31, v180
	v_lshlrev_b64 v[130:131], 11, v[184:185]
	v_lshlrev_b64 v[132:133], 11, v[180:181]
	v_lshl_add_u64 v[130:131], s[28:29], 0, v[130:131]
	v_lshl_add_u64 v[132:133], s[28:29], 0, v[132:133]
	v_lshl_add_u64 v[58:59], v[130:131], 0, v[194:195]
	v_lshl_add_u64 v[132:133], v[132:133], 0, v[194:195]
	s_waitcnt lgkmcnt(0)
	v_add_f32_e32 v50, v201, v50
	v_add_f32_e32 v51, v175, v51
	ds_bpermute_b32 v53, v199, v50
	ds_bpermute_b32 v54, v199, v51
	s_waitcnt lgkmcnt(0)
	v_add_f32_e32 v50, v50, v53
	v_add_f32_e32 v51, v51, v54
	v_div_scale_f32 v134, s[0:1], v50, v50, 1.0
	v_rcp_f32_e32 v135, v134
	s_nop 0
	v_fma_f32 v136, -v134, v135, 1.0
	v_fmac_f32_e32 v135, v136, v135
	v_div_scale_f32 v136, vcc, 1.0, v50, 1.0
	v_mul_f32_e32 v137, v136, v135
	v_fma_f32 v138, -v134, v137, v136
	v_fmac_f32_e32 v137, v138, v135
	v_fma_f32 v134, -v134, v137, v136
	v_div_fmas_f32 v134, v134, v135, v137
	v_div_fixup_f32 v66, v134, v50, 1.0
	v_div_scale_f32 v134, s[0:1], v51, v51, 1.0
	v_rcp_f32_e32 v135, v134
	s_nop 0
	v_fma_f32 v136, -v134, v135, 1.0
	v_fmac_f32_e32 v135, v136, v135
	v_div_scale_f32 v136, vcc, 1.0, v51, 1.0
	v_mul_f32_e32 v137, v136, v135
	v_fma_f32 v138, -v134, v137, v136
	v_fmac_f32_e32 v137, v138, v135
	v_fma_f32 v134, -v134, v137, v136
	v_div_fmas_f32 v134, v134, v135, v137
	v_div_fixup_f32 v67, v134, v51, 1.0
	s_waitcnt vmcnt(0)
	v_mul_f32_e32 v140, v90, v66
	v_lshlrev_b32_e32 v141, 16, v98
	v_mul_f32_e32 v142, v91, v66
	v_and_b32_e32 v143, 0xffff0000, v98
	v_mul_f32_e32 v140, v140, v141
	v_mul_f32_e32 v142, v142, v143
	v_mul_f32_e32 v144, v92, v66
	v_lshlrev_b32_e32 v145, 16, v99
	v_mul_f32_e32 v146, v93, v66
	v_and_b32_e32 v147, 0xffff0000, v99
	v_mul_f32_e32 v144, v144, v145
	v_mul_f32_e32 v146, v146, v147
	v_cvt_pk_bf16_f32 v98, v140, v142
	v_cvt_pk_bf16_f32 v99, v144, v146
	global_store_dwordx2 v[58:59], v[98:99], off
	v_mul_f32_e32 v140, v74, v66
	v_lshlrev_b32_e32 v141, 16, v100
	v_mul_f32_e32 v142, v75, v66
	v_and_b32_e32 v143, 0xffff0000, v100
	v_mul_f32_e32 v140, v140, v141
	v_mul_f32_e32 v142, v142, v143
	v_mul_f32_e32 v144, v76, v66
	v_lshlrev_b32_e32 v145, 16, v101
	v_mul_f32_e32 v146, v77, v66
	v_and_b32_e32 v147, 0xffff0000, v101
	v_mul_f32_e32 v144, v144, v145
	v_mul_f32_e32 v146, v146, v147
	v_cvt_pk_bf16_f32 v100, v140, v142
	v_cvt_pk_bf16_f32 v101, v144, v146
	global_store_dwordx2 v[58:59], v[100:101], off offset:32
	v_mul_f32_e32 v140, v70, v66
	v_lshlrev_b32_e32 v141, 16, v102
	v_mul_f32_e32 v142, v71, v66
	v_and_b32_e32 v143, 0xffff0000, v102
	v_mul_f32_e32 v140, v140, v141
	v_mul_f32_e32 v142, v142, v143
	v_mul_f32_e32 v144, v72, v66
	v_lshlrev_b32_e32 v145, 16, v103
	v_mul_f32_e32 v146, v73, v66
	v_and_b32_e32 v147, 0xffff0000, v103
	v_mul_f32_e32 v144, v144, v145
	v_mul_f32_e32 v146, v146, v147
	v_cvt_pk_bf16_f32 v102, v140, v142
	v_cvt_pk_bf16_f32 v103, v144, v146
	global_store_dwordx2 v[58:59], v[102:103], off offset:64
	v_mul_f32_e32 v140, v62, v66
	v_lshlrev_b32_e32 v141, 16, v104
	v_mul_f32_e32 v142, v63, v66
	v_and_b32_e32 v143, 0xffff0000, v104
	v_mul_f32_e32 v140, v140, v141
	v_mul_f32_e32 v142, v142, v143
	v_mul_f32_e32 v144, v64, v66
	v_lshlrev_b32_e32 v145, 16, v105
	v_mul_f32_e32 v146, v65, v66
	v_and_b32_e32 v147, 0xffff0000, v105
	v_mul_f32_e32 v144, v144, v145
	v_mul_f32_e32 v146, v146, v147
	v_cvt_pk_bf16_f32 v104, v140, v142
	v_cvt_pk_bf16_f32 v105, v144, v146
	global_store_dwordx2 v[58:59], v[104:105], off offset:96
	v_mul_f32_e32 v140, v46, v66
	v_lshlrev_b32_e32 v141, 16, v106
	v_mul_f32_e32 v142, v47, v66
	v_and_b32_e32 v143, 0xffff0000, v106
	v_mul_f32_e32 v140, v140, v141
	v_mul_f32_e32 v142, v142, v143
	v_mul_f32_e32 v144, v48, v66
	v_lshlrev_b32_e32 v145, 16, v107
	v_mul_f32_e32 v146, v49, v66
	v_and_b32_e32 v147, 0xffff0000, v107
	v_mul_f32_e32 v144, v144, v145
	v_mul_f32_e32 v146, v146, v147
	v_cvt_pk_bf16_f32 v106, v140, v142
	v_cvt_pk_bf16_f32 v107, v144, v146
	global_store_dwordx2 v[58:59], v[106:107], off offset:128
	v_mul_f32_e32 v140, v42, v66
	v_lshlrev_b32_e32 v141, 16, v108
	v_mul_f32_e32 v142, v43, v66
	v_and_b32_e32 v143, 0xffff0000, v108
	v_mul_f32_e32 v140, v140, v141
	v_mul_f32_e32 v142, v142, v143
	v_mul_f32_e32 v144, v44, v66
	v_lshlrev_b32_e32 v145, 16, v109
	v_mul_f32_e32 v146, v45, v66
	v_and_b32_e32 v147, 0xffff0000, v109
	v_mul_f32_e32 v144, v144, v145
	v_mul_f32_e32 v146, v146, v147
	v_cvt_pk_bf16_f32 v108, v140, v142
	v_cvt_pk_bf16_f32 v109, v144, v146
	global_store_dwordx2 v[58:59], v[108:109], off offset:160
	v_mul_f32_e32 v140, v38, v66
	v_lshlrev_b32_e32 v141, 16, v110
	v_mul_f32_e32 v142, v39, v66
	v_and_b32_e32 v143, 0xffff0000, v110
	v_mul_f32_e32 v140, v140, v141
	v_mul_f32_e32 v142, v142, v143
	v_mul_f32_e32 v144, v40, v66
	v_lshlrev_b32_e32 v145, 16, v111
	v_mul_f32_e32 v146, v41, v66
	v_and_b32_e32 v147, 0xffff0000, v111
	v_mul_f32_e32 v144, v144, v145
	v_mul_f32_e32 v146, v146, v147
	v_cvt_pk_bf16_f32 v110, v140, v142
	v_cvt_pk_bf16_f32 v111, v144, v146
	global_store_dwordx2 v[58:59], v[110:111], off offset:192
	v_mul_f32_e32 v140, v34, v66
	v_lshlrev_b32_e32 v141, 16, v112
	v_mul_f32_e32 v142, v35, v66
	v_and_b32_e32 v143, 0xffff0000, v112
	v_mul_f32_e32 v140, v140, v141
	v_mul_f32_e32 v142, v142, v143
	v_mul_f32_e32 v144, v36, v66
	v_lshlrev_b32_e32 v145, 16, v113
	v_mul_f32_e32 v146, v37, v66
	v_and_b32_e32 v147, 0xffff0000, v113
	v_mul_f32_e32 v144, v144, v145
	v_mul_f32_e32 v146, v146, v147
	v_cvt_pk_bf16_f32 v112, v140, v142
	v_cvt_pk_bf16_f32 v113, v144, v146
	global_store_dwordx2 v[58:59], v[112:113], off offset:224
	v_mul_f32_e32 v140, v30, v67
	v_lshlrev_b32_e32 v141, 16, v114
	v_mul_f32_e32 v142, v31, v67
	v_and_b32_e32 v143, 0xffff0000, v114
	v_mul_f32_e32 v140, v140, v141
	v_mul_f32_e32 v142, v142, v143
	v_mul_f32_e32 v144, v32, v67
	v_lshlrev_b32_e32 v145, 16, v115
	v_mul_f32_e32 v146, v33, v67
	v_and_b32_e32 v147, 0xffff0000, v115
	v_mul_f32_e32 v144, v144, v145
	v_mul_f32_e32 v146, v146, v147
	v_cvt_pk_bf16_f32 v114, v140, v142
	v_cvt_pk_bf16_f32 v115, v144, v146
	global_store_dwordx2 v[132:133], v[114:115], off
	v_mul_f32_e32 v140, v26, v67
	v_lshlrev_b32_e32 v141, 16, v116
	v_mul_f32_e32 v142, v27, v67
	v_and_b32_e32 v143, 0xffff0000, v116
	v_mul_f32_e32 v140, v140, v141
	v_mul_f32_e32 v142, v142, v143
	v_mul_f32_e32 v144, v28, v67
	v_lshlrev_b32_e32 v145, 16, v117
	v_mul_f32_e32 v146, v29, v67
	v_and_b32_e32 v147, 0xffff0000, v117
	v_mul_f32_e32 v144, v144, v145
	v_mul_f32_e32 v146, v146, v147
	v_cvt_pk_bf16_f32 v116, v140, v142
	v_cvt_pk_bf16_f32 v117, v144, v146
	global_store_dwordx2 v[132:133], v[116:117], off offset:32
	v_mul_f32_e32 v140, v22, v67
	v_lshlrev_b32_e32 v141, 16, v118
	v_mul_f32_e32 v142, v23, v67
	v_and_b32_e32 v143, 0xffff0000, v118
	v_mul_f32_e32 v140, v140, v141
	v_mul_f32_e32 v142, v142, v143
	v_mul_f32_e32 v144, v24, v67
	v_lshlrev_b32_e32 v145, 16, v119
	v_mul_f32_e32 v146, v25, v67
	v_and_b32_e32 v147, 0xffff0000, v119
	v_mul_f32_e32 v144, v144, v145
	v_mul_f32_e32 v146, v146, v147
	v_cvt_pk_bf16_f32 v118, v140, v142
	v_cvt_pk_bf16_f32 v119, v144, v146
	global_store_dwordx2 v[132:133], v[118:119], off offset:64
	v_mul_f32_e32 v140, v18, v67
	v_lshlrev_b32_e32 v141, 16, v120
	v_mul_f32_e32 v142, v19, v67
	v_and_b32_e32 v143, 0xffff0000, v120
	v_mul_f32_e32 v140, v140, v141
	v_mul_f32_e32 v142, v142, v143
	v_mul_f32_e32 v144, v20, v67
	v_lshlrev_b32_e32 v145, 16, v121
	v_mul_f32_e32 v146, v21, v67
	v_and_b32_e32 v147, 0xffff0000, v121
	v_mul_f32_e32 v144, v144, v145
	v_mul_f32_e32 v146, v146, v147
	v_cvt_pk_bf16_f32 v120, v140, v142
	v_cvt_pk_bf16_f32 v121, v144, v146
	global_store_dwordx2 v[132:133], v[120:121], off offset:96
	v_mul_f32_e32 v140, v14, v67
	v_lshlrev_b32_e32 v141, 16, v122
	v_mul_f32_e32 v142, v15, v67
	v_and_b32_e32 v143, 0xffff0000, v122
	v_mul_f32_e32 v140, v140, v141
	v_mul_f32_e32 v142, v142, v143
	v_mul_f32_e32 v144, v16, v67
	v_lshlrev_b32_e32 v145, 16, v123
	v_mul_f32_e32 v146, v17, v67
	v_and_b32_e32 v147, 0xffff0000, v123
	v_mul_f32_e32 v144, v144, v145
	v_mul_f32_e32 v146, v146, v147
	v_cvt_pk_bf16_f32 v122, v140, v142
	v_cvt_pk_bf16_f32 v123, v144, v146
	global_store_dwordx2 v[132:133], v[122:123], off offset:128
	v_mul_f32_e32 v140, v10, v67
	v_lshlrev_b32_e32 v141, 16, v124
	v_mul_f32_e32 v142, v11, v67
	v_and_b32_e32 v143, 0xffff0000, v124
	v_mul_f32_e32 v140, v140, v141
	v_mul_f32_e32 v142, v142, v143
	v_mul_f32_e32 v144, v12, v67
	v_lshlrev_b32_e32 v145, 16, v125
	v_mul_f32_e32 v146, v13, v67
	v_and_b32_e32 v147, 0xffff0000, v125
	v_mul_f32_e32 v144, v144, v145
	v_mul_f32_e32 v146, v146, v147
	v_cvt_pk_bf16_f32 v124, v140, v142
	v_cvt_pk_bf16_f32 v125, v144, v146
	global_store_dwordx2 v[132:133], v[124:125], off offset:160
	v_mul_f32_e32 v140, v6, v67
	v_lshlrev_b32_e32 v141, 16, v126
	v_mul_f32_e32 v142, v7, v67
	v_and_b32_e32 v143, 0xffff0000, v126
	v_mul_f32_e32 v140, v140, v141
	v_mul_f32_e32 v142, v142, v143
	v_mul_f32_e32 v144, v8, v67
	v_lshlrev_b32_e32 v145, 16, v127
	v_mul_f32_e32 v146, v9, v67
	v_and_b32_e32 v147, 0xffff0000, v127
	v_mul_f32_e32 v144, v144, v145
	v_mul_f32_e32 v146, v146, v147
	v_cvt_pk_bf16_f32 v126, v140, v142
	v_cvt_pk_bf16_f32 v127, v144, v146
	global_store_dwordx2 v[132:133], v[126:127], off offset:192
	v_mul_f32_e32 v140, v2, v67
	v_lshlrev_b32_e32 v141, 16, v128
	v_mul_f32_e32 v142, v3, v67
	v_and_b32_e32 v143, 0xffff0000, v128
	v_mul_f32_e32 v140, v140, v141
	v_mul_f32_e32 v142, v142, v143
	v_mul_f32_e32 v144, v4, v67
	v_lshlrev_b32_e32 v145, 16, v129
	v_mul_f32_e32 v146, v5, v67
	v_and_b32_e32 v147, 0xffff0000, v129
	v_mul_f32_e32 v144, v144, v145
	v_mul_f32_e32 v146, v146, v147
	v_cvt_pk_bf16_f32 v128, v140, v142
	v_cvt_pk_bf16_f32 v129, v144, v146
	global_store_dwordx2 v[132:133], v[128:129], off offset:224
	s_add_i32 s34, s34, s88
	s_add_i32 s26, s26, s79
	s_cmpk_gt_i32 s34, 0xfff
	s_cbranch_scc1 .LBB0_328
.LBB0_281:
	s_and_b32 s23, s34, 0xfffffe07
	s_and_b32 s27, s34, 0x38
	s_lshl_b32 s27, s27, 3
	s_or_b32 s23, s23, s27
	s_and_b32 s27, s34, 0x1c0
	s_lshr_b32 s27, s27, 3
	s_or_b32 s23, s23, s27
	s_lshr_b32 s0, s23, 1
	s_and_b32 s6, s0, 30
	s_ashr_i32 s4, s23, 9
	s_lshl_b32 s5, s4, 11
	s_lshl_b32 s1, s6, 6
	s_or_b32 s7, s1, s5
	s_lshl_b32 s1, s23, 4
	s_and_b32 s1, s1, 48
	s_or_b32 s7, s7, s1
	s_bfe_u32 s0, s23, 0x30006
	v_or_b32_e32 v184, s7, v192
	v_mov_b64_e32 v[30:31], s[50:51]
	v_mad_i64_i32 v[186:187], s[8:9], v184, s37, v[30:31]
	s_lshl_b32 s42, s0, 8
	v_lshl_add_u64 v[2:3], v[186:187], 0, s[42:43]
	v_lshlrev_b32_e32 v194, 1, v170
	v_lshl_add_u64 v[6:7], v[2:3], 0, v[194:195]
	v_add_co_u32_e32 v2, vcc, s91, v6
	v_lshl_add_u64 v[14:15], v[6:7], 0, s[10:11]
	s_nop 0
	v_addc_co_u32_e32 v3, vcc, 0, v7, vcc
	global_load_dwordx4 v[2:5], v[2:3], off
	s_nop 0
	global_load_dwordx4 v[6:9], v[14:15], off offset:64
	global_load_dwordx4 v[10:13], v[14:15], off offset:128
	global_load_dwordx4 v[18:21], v[14:15], off offset:192
	global_load_dwordx4 v[22:25], v[176:177], off offset:16
	global_load_dwordx4 v[26:29], v[176:177], off
	v_or_b32_e32 v180, 64, v184
	v_mad_i64_i32 v[182:183], s[8:9], v180, s37, v[30:31]
	v_sub_u32_e64 v111, s6, 3 clamp
	v_sub_u32_e64 v112, s6, 4 clamp
	v_readfirstlane_b32 s6, v111
	v_readfirstlane_b32 s7, v112
	s_min_u32 s14, s6, 24
	s_min_u32 s15, s7, 24
	s_sub_i32 s59, s14, s15
	s_lshl_b32 s13, s0, 7
	s_add_i32 s2, s59, 8
	s_cmp_lt_i32 s2, -7
	s_waitcnt vmcnt(0)
	v_lshlrev_b32_e32 v42, 16, v6
	v_and_b32_e32 v43, 0xffff0000, v6
	v_and_b32_e32 v16, 0xffff0000, v18
	v_and_b32_e32 v35, 0xffff0000, v2
	v_lshlrev_b32_e32 v34, 16, v2
	v_lshlrev_b32_e32 v17, 16, v18
	v_mul_f32_e32 v18, v35, v35
	v_lshlrev_b32_e32 v36, 16, v3
	v_fmac_f32_e32 v18, v34, v34
	v_and_b32_e32 v37, 0xffff0000, v3
	v_fmac_f32_e32 v18, v36, v36
	v_lshlrev_b32_e32 v38, 16, v4
	v_fmac_f32_e32 v18, v37, v37
	v_and_b32_e32 v39, 0xffff0000, v4
	v_fmac_f32_e32 v18, v38, v38
	v_lshlrev_b32_e32 v40, 16, v5
	v_fmac_f32_e32 v18, v39, v39
	v_and_b32_e32 v41, 0xffff0000, v5
	v_fmac_f32_e32 v18, v40, v40
	v_fmac_f32_e32 v18, v41, v41
	v_fmac_f32_e32 v18, v42, v42
	v_lshlrev_b32_e32 v44, 16, v7
	v_fmac_f32_e32 v18, v43, v43
	v_and_b32_e32 v45, 0xffff0000, v7
	v_fmac_f32_e32 v18, v44, v44
	v_lshlrev_b32_e32 v46, 16, v8
	v_fmac_f32_e32 v18, v45, v45
	v_and_b32_e32 v47, 0xffff0000, v8
	v_fmac_f32_e32 v18, v46, v46
	v_lshlrev_b32_e32 v48, 16, v9
	v_fmac_f32_e32 v18, v47, v47
	v_and_b32_e32 v49, 0xffff0000, v9
	v_fmac_f32_e32 v18, v48, v48
	v_lshlrev_b32_e32 v58, 16, v10
	v_fmac_f32_e32 v18, v49, v49
	v_and_b32_e32 v59, 0xffff0000, v10
	v_fmac_f32_e32 v18, v58, v58
	v_lshlrev_b32_e32 v60, 16, v11
	v_fmac_f32_e32 v18, v59, v59
	v_and_b32_e32 v61, 0xffff0000, v11
	v_fmac_f32_e32 v18, v60, v60
	v_lshlrev_b32_e32 v62, 16, v12
	v_fmac_f32_e32 v18, v61, v61
	v_and_b32_e32 v63, 0xffff0000, v12
	v_fmac_f32_e32 v18, v62, v62
	v_lshlrev_b32_e32 v64, 16, v13
	v_fmac_f32_e32 v18, v63, v63
	v_and_b32_e32 v65, 0xffff0000, v13
	v_fmac_f32_e32 v18, v64, v64
	v_pk_mul_f32 v[2:3], v[16:17], v[16:17]
	v_fmac_f32_e32 v18, v65, v65
	v_and_b32_e32 v14, 0xffff0000, v19
	v_lshlrev_b32_e32 v15, 16, v19
	v_add_f32_e32 v3, v3, v18
	v_pk_mul_f32 v[4:5], v[14:15], v[14:15]
	v_add_f32_e32 v2, v2, v3
	v_and_b32_e32 v12, 0xffff0000, v20
	v_lshlrev_b32_e32 v13, 16, v20
	v_add_f32_e32 v2, v5, v2
	v_pk_mul_f32 v[6:7], v[12:13], v[12:13]
	v_add_f32_e32 v2, v4, v2
	v_and_b32_e32 v10, 0xffff0000, v21
	v_lshlrev_b32_e32 v11, 16, v21
	v_add_f32_e32 v2, v7, v2
	v_pk_mul_f32 v[8:9], v[10:11], v[10:11]
	v_add_f32_e32 v2, v6, v2
	v_add_f32_e32 v2, v9, v2
	v_add_f32_e32 v6, v8, v2
	ds_bpermute_b32 v7, v171, v6
	v_lshl_add_u64 v[2:3], v[182:183], 0, s[42:43]
	v_lshl_add_u64 v[2:3], v[2:3], 0, v[194:195]
	v_lshl_add_u64 v[4:5], v[2:3], 0, s[10:11]
	v_add_co_u32_e32 v2, vcc, s91, v2
	s_waitcnt lgkmcnt(0)
	v_add_f32_e32 v6, v6, v7
	ds_bpermute_b32 v7, v199, v6
	v_addc_co_u32_e32 v3, vcc, 0, v3, vcc
	s_waitcnt lgkmcnt(0)
	v_add_f32_e32 v6, v6, v7
	v_fmamk_f32 v6, v6, 0x3c000000, v230
	v_mul_f32_e32 v7, 0x4b800000, v6
	v_cmp_gt_f32_e32 vcc, s70, v6
	s_nop 1
	v_cndmask_b32_e32 v6, v6, v7, vcc
	v_rsq_f32_e32 v50, v6
	global_load_dwordx4 v[18:21], v[4:5], off offset:64
	global_load_dwordx4 v[6:9], v[4:5], off offset:128
	global_load_dwordx4 v[30:33], v[2:3], off
	s_nop 0
	global_load_dwordx4 v[2:5], v[4:5], off offset:192
	v_mul_f32_e32 v51, 0x45800000, v50
	v_cndmask_b32_e32 v50, v50, v51, vcc
	v_mul_f32_e32 v66, 0x3db504f3, v50
	v_mul_f32_e32 v34, v66, v34
	v_mul_f32_e32 v35, v66, v35
	v_mul_f32_e32 v36, v66, v36
	v_mul_f32_e32 v37, v66, v37
	v_mul_f32_e32 v38, v66, v38
	v_mul_f32_e32 v39, v66, v39
	v_mul_f32_e32 v40, v66, v40
	v_mul_f32_e32 v41, v66, v41
	v_mul_f32_e32 v26, v26, v34
	v_mul_f32_e32 v27, v27, v35
	v_mul_f32_e32 v28, v28, v36
	v_mul_f32_e32 v29, v29, v37
	v_mul_f32_e32 v22, v22, v38
	v_mul_f32_e32 v23, v23, v39
	v_mul_f32_e32 v24, v24, v40
	v_mul_f32_e32 v25, v25, v41
	v_cvt_pk_bf16_f32 v50, v26, v27
	v_cvt_pk_bf16_f32 v51, v28, v29
	v_cvt_pk_bf16_f32 v52, v22, v23
	v_cvt_pk_bf16_f32 v53, v24, v25
	global_load_dwordx4 v[22:25], v[176:177], off offset:128
	global_load_dwordx4 v[26:29], v[176:177], off offset:144
	v_mul_f32_e32 v34, v66, v42
	v_mul_f32_e32 v35, v66, v43
	v_mul_f32_e32 v36, v66, v44
	v_mul_f32_e32 v37, v66, v45
	v_mul_f32_e32 v38, v66, v46
	v_mul_f32_e32 v39, v66, v47
	v_mul_f32_e32 v40, v66, v48
	v_mul_f32_e32 v41, v66, v49
	v_mul_f32_e32 v15, v66, v15
	v_mul_f32_e32 v14, v66, v14
	v_mul_f32_e32 v13, v66, v13
	v_mul_f32_e32 v12, v66, v12
	v_mul_f32_e32 v11, v66, v11
	v_mul_f32_e32 v10, v66, v10
	s_waitcnt vmcnt(4)
	v_lshlrev_b32_e32 v42, 16, v6
	v_and_b32_e32 v43, 0xffff0000, v6
	v_lshlrev_b32_e32 v44, 16, v7
	v_and_b32_e32 v45, 0xffff0000, v7
	v_mul_f32_e32 v6, v66, v17
	v_mul_f32_e32 v7, v66, v16
	s_waitcnt vmcnt(2)
	v_and_b32_e32 v98, 0xffff0000, v2
	v_lshlrev_b32_e32 v99, 16, v2
	v_and_b32_e32 v96, 0xffff0000, v3
	v_lshlrev_b32_e32 v97, 16, v3
	v_pk_mul_f32 v[2:3], v[98:99], v[98:99]
	v_and_b32_e32 v94, 0xffff0000, v4
	v_lshlrev_b32_e32 v95, 16, v4
	v_and_b32_e32 v100, 0xffff0000, v5
	v_lshlrev_b32_e32 v101, 16, v5
	v_pk_mul_f32 v[4:5], v[96:97], v[96:97]
	s_waitcnt vmcnt(1)
	v_mul_f32_e32 v22, v22, v34
	v_mul_f32_e32 v23, v23, v35
	v_mul_f32_e32 v24, v24, v36
	v_mul_f32_e32 v25, v25, v37
	s_waitcnt vmcnt(0)
	v_mul_f32_e32 v26, v26, v38
	v_mul_f32_e32 v27, v27, v39
	v_mul_f32_e32 v28, v28, v40
	v_mul_f32_e32 v29, v29, v41
	v_cvt_pk_bf16_f32 v54, v22, v23
	v_cvt_pk_bf16_f32 v55, v24, v25
	v_cvt_pk_bf16_f32 v56, v26, v27
	v_cvt_pk_bf16_f32 v57, v28, v29
	global_load_dwordx4 v[22:25], v[176:177], off offset:256
	global_load_dwordx4 v[26:29], v[176:177], off offset:272
	v_mul_f32_e32 v34, v66, v58
	v_mul_f32_e32 v35, v66, v59
	v_mul_f32_e32 v36, v66, v60
	v_mul_f32_e32 v37, v66, v61
	v_mul_f32_e32 v38, v66, v62
	v_mul_f32_e32 v39, v66, v63
	v_mul_f32_e32 v40, v66, v64
	v_mul_f32_e32 v41, v66, v65
	s_waitcnt vmcnt(1)
	v_mul_f32_e32 v22, v22, v34
	v_mul_f32_e32 v23, v23, v35
	v_mul_f32_e32 v24, v24, v36
	v_mul_f32_e32 v25, v25, v37
	s_waitcnt vmcnt(0)
	v_mul_f32_e32 v26, v26, v38
	v_mul_f32_e32 v27, v27, v39
	v_mul_f32_e32 v28, v28, v40
	v_mul_f32_e32 v29, v29, v41
	v_cvt_pk_bf16_f32 v58, v22, v23
	v_cvt_pk_bf16_f32 v59, v24, v25
	v_cvt_pk_bf16_f32 v60, v26, v27
	v_cvt_pk_bf16_f32 v61, v28, v29
	global_load_dwordx4 v[22:25], v[176:177], off offset:384
	global_load_dwordx4 v[26:29], v[176:177], off offset:400
	v_lshlrev_b32_e32 v34, 16, v30
	v_and_b32_e32 v30, 0xffff0000, v30
	v_lshlrev_b32_e32 v35, 16, v31
	v_and_b32_e32 v31, 0xffff0000, v31
	v_lshlrev_b32_e32 v36, 16, v32
	v_and_b32_e32 v32, 0xffff0000, v32
	v_lshlrev_b32_e32 v37, 16, v33
	v_and_b32_e32 v33, 0xffff0000, v33
	v_lshlrev_b32_e32 v38, 16, v18
	v_and_b32_e32 v18, 0xffff0000, v18
	v_lshlrev_b32_e32 v39, 16, v19
	v_and_b32_e32 v19, 0xffff0000, v19
	v_lshlrev_b32_e32 v40, 16, v20
	v_and_b32_e32 v20, 0xffff0000, v20
	v_lshlrev_b32_e32 v41, 16, v21
	v_and_b32_e32 v21, 0xffff0000, v21
	s_waitcnt vmcnt(1)
	v_mul_f32_e32 v15, v24, v15
	v_mul_f32_e32 v14, v25, v14
	s_waitcnt vmcnt(0)
	v_mul_f32_e32 v13, v26, v13
	v_mul_f32_e32 v12, v27, v12
	v_mul_f32_e32 v11, v28, v11
	v_mul_f32_e32 v10, v29, v10
	v_mul_f32_e32 v6, v22, v6
	v_mul_f32_e32 v7, v23, v7
	v_cvt_pk_bf16_f32 v66, v6, v7
	v_cvt_pk_bf16_f32 v67, v15, v14
	v_cvt_pk_bf16_f32 v68, v13, v12
	v_cvt_pk_bf16_f32 v69, v11, v10
	global_load_dwordx4 v[10:13], v[176:177], off offset:16
	global_load_dwordx4 v[14:17], v[176:177], off
	v_mul_f32_e32 v26, v30, v30
	v_fmac_f32_e32 v26, v34, v34
	v_fmac_f32_e32 v26, v35, v35
	v_fmac_f32_e32 v26, v31, v31
	v_fmac_f32_e32 v26, v36, v36
	v_fmac_f32_e32 v26, v32, v32
	v_fmac_f32_e32 v26, v37, v37
	v_fmac_f32_e32 v26, v33, v33
	v_fmac_f32_e32 v26, v38, v38
	v_fmac_f32_e32 v26, v18, v18
	v_fmac_f32_e32 v26, v39, v39
	v_fmac_f32_e32 v26, v19, v19
	v_fmac_f32_e32 v26, v40, v40
	v_fmac_f32_e32 v26, v20, v20
	v_fmac_f32_e32 v26, v41, v41
	v_fmac_f32_e32 v26, v21, v21
	v_fmac_f32_e32 v26, v42, v42
	v_fmac_f32_e32 v26, v43, v43
	v_fmac_f32_e32 v26, v44, v44
	v_lshlrev_b32_e32 v22, 16, v8
	v_fmac_f32_e32 v26, v45, v45
	v_and_b32_e32 v23, 0xffff0000, v8
	v_fmac_f32_e32 v26, v22, v22
	v_lshlrev_b32_e32 v24, 16, v9
	v_fmac_f32_e32 v26, v23, v23
	v_and_b32_e32 v25, 0xffff0000, v9
	v_fmac_f32_e32 v26, v24, v24
	v_fmac_f32_e32 v26, v25, v25
	v_add_f32_e32 v3, v3, v26
	v_add_f32_e32 v2, v2, v3
	v_add_f32_e32 v2, v5, v2
	v_pk_mul_f32 v[6:7], v[94:95], v[94:95]
	v_add_f32_e32 v2, v4, v2
	v_add_f32_e32 v2, v7, v2
	v_pk_mul_f32 v[8:9], v[100:101], v[100:101]
	v_add_f32_e32 v2, v6, v2
	v_add_f32_e32 v2, v9, v2
	v_add_f32_e32 v2, v8, v2
	ds_bpermute_b32 v3, v171, v2
	s_waitcnt lgkmcnt(0)
	v_add_f32_e32 v2, v2, v3
	ds_bpermute_b32 v3, v199, v2
	s_waitcnt lgkmcnt(0)
	v_add_f32_e32 v2, v2, v3
	v_fmamk_f32 v2, v2, 0x3c000000, v230
	v_mul_f32_e32 v3, 0x4b800000, v2
	v_cmp_gt_f32_e32 vcc, s70, v2
	s_nop 1
	v_cndmask_b32_e32 v2, v2, v3, vcc
	v_rsq_f32_e32 v2, v2
	s_nop 0
	v_mul_f32_e32 v3, 0x45800000, v2
	v_cndmask_b32_e32 v2, v2, v3, vcc
	v_mul_f32_e32 v110, 0x3db504f3, v2
	v_mul_f32_e32 v2, v110, v34
	v_mul_f32_e32 v3, v110, v30
	v_mul_f32_e32 v4, v110, v35
	v_mul_f32_e32 v5, v110, v31
	v_mul_f32_e32 v6, v110, v36
	v_mul_f32_e32 v7, v110, v32
	v_mul_f32_e32 v8, v110, v37
	v_mul_f32_e32 v9, v110, v33
	v_mul_f32_e32 v97, v110, v97
	v_mul_f32_e32 v96, v110, v96
	v_mul_f32_e32 v99, v110, v99
	v_mul_f32_e32 v98, v110, v98
	v_mul_f32_e32 v95, v110, v95
	v_mul_f32_e32 v94, v110, v94
	v_mul_f32_e32 v101, v110, v101
	s_waitcnt vmcnt(1)
	v_mul_f32_e32 v6, v10, v6
	s_waitcnt vmcnt(0)
	v_mul_f32_e32 v2, v14, v2
	v_mul_f32_e32 v3, v15, v3
	v_mul_f32_e32 v4, v16, v4
	v_mul_f32_e32 v5, v17, v5
	v_mul_f32_e32 v7, v11, v7
	v_mul_f32_e32 v8, v12, v8
	v_mul_f32_e32 v9, v13, v9
	v_cvt_pk_bf16_f32 v78, v2, v3
	v_cvt_pk_bf16_f32 v79, v4, v5
	v_cvt_pk_bf16_f32 v80, v6, v7
	v_cvt_pk_bf16_f32 v81, v8, v9
	global_load_dwordx4 v[2:5], v[176:177], off offset:128
	global_load_dwordx4 v[6:9], v[176:177], off offset:144
	v_mul_f32_e32 v14, v110, v40
	v_mul_f32_e32 v15, v110, v20
	v_mul_f32_e32 v16, v110, v41
	v_mul_f32_e32 v17, v110, v21
	v_mul_f32_e32 v10, v110, v38
	v_mul_f32_e32 v11, v110, v18
	v_mul_f32_e32 v12, v110, v39
	v_mul_f32_e32 v13, v110, v19
	v_mul_f32_e32 v18, v110, v23
	v_mul_f32_e32 v19, v110, v24
	v_mul_f32_e32 v20, v110, v25
	v_mul_f32_e32 v100, v110, v100
	s_waitcnt vmcnt(1)
	v_mul_f32_e32 v2, v2, v10
	s_waitcnt vmcnt(0)
	v_mul_f32_e32 v6, v6, v14
	v_mul_f32_e32 v7, v7, v15
	v_mul_f32_e32 v8, v8, v16
	v_mul_f32_e32 v9, v9, v17
	v_mul_f32_e32 v3, v3, v11
	v_mul_f32_e32 v4, v4, v12
	v_mul_f32_e32 v5, v5, v13
	v_cvt_pk_bf16_f32 v82, v2, v3
	v_cvt_pk_bf16_f32 v83, v4, v5
	v_cvt_pk_bf16_f32 v84, v6, v7
	v_cvt_pk_bf16_f32 v85, v8, v9
	global_load_dwordx4 v[6:9], v[176:177], off offset:256
	global_load_dwordx4 v[10:13], v[176:177], off offset:272
	v_mul_f32_e32 v2, v110, v42
	v_mul_f32_e32 v14, v110, v43
	v_mul_f32_e32 v15, v110, v44
	v_mul_f32_e32 v16, v110, v45
	v_mul_f32_e32 v17, v110, v22
	v_mov_b32_e32 v5, 0
	v_mov_b32_e32 v4, v5
	v_mov_b32_e32 v3, v5
	v_mov_b32_e32 v21, v5
	v_mov_b32_e32 v25, v5
	v_mov_b32_e32 v24, v5
	v_mov_b32_e32 v23, v5
	v_mov_b32_e32 v22, v5
	v_mov_b32_e32 v29, v5
	v_mov_b32_e32 v28, v5
	v_mov_b32_e32 v27, v5
	v_mov_b32_e32 v26, v5
	v_mov_b32_e32 v33, v5
	v_mov_b32_e32 v32, v5
	v_mov_b32_e32 v31, v5
	v_mov_b32_e32 v30, v5
	v_mov_b32_e32 v93, v5
	v_mov_b32_e32 v92, v5
	v_mov_b32_e32 v91, v5
	v_mov_b32_e32 v90, v5
	v_mov_b32_e32 v77, v5
	v_mov_b32_e32 v76, v5
	v_mov_b32_e32 v75, v5
	v_mov_b32_e32 v74, v5
	v_mov_b32_e32 v73, v5
	v_mov_b32_e32 v72, v5
	v_mov_b32_e32 v71, v5
	v_mov_b32_e32 v70, v5
	v_mov_b32_e32 v65, v5
	v_mov_b32_e32 v64, v5
	v_mov_b32_e32 v63, v5
	v_mov_b32_e32 v62, v5
	v_mov_b32_e32 v49, v5
	v_mov_b32_e32 v48, v5
	v_mov_b32_e32 v47, v5
	v_mov_b32_e32 v46, v5
	v_mov_b32_e32 v45, v5
	v_mov_b32_e32 v44, v5
	v_mov_b32_e32 v43, v5
	v_mov_b32_e32 v42, v5
	v_mov_b32_e32 v41, v5
	v_mov_b32_e32 v40, v5
	v_mov_b32_e32 v39, v5
	v_mov_b32_e32 v38, v5
	v_mov_b32_e32 v37, v5
	v_mov_b32_e32 v36, v5
	v_mov_b32_e32 v35, v5
	v_mov_b32_e32 v34, v5
	v_mov_b32_e32 v201, v5
	v_mov_b32_e32 v175, v5
	s_waitcnt vmcnt(1)
	v_mul_f32_e32 v2, v2, v6
	v_mul_f32_e32 v6, v14, v7
	v_mul_f32_e32 v7, v15, v8
	v_mul_f32_e32 v8, v16, v9
	s_waitcnt vmcnt(0)
	v_mul_f32_e32 v9, v17, v10
	v_mul_f32_e32 v10, v18, v11
	v_mul_f32_e32 v11, v19, v12
	v_mul_f32_e32 v12, v20, v13
	v_cvt_pk_bf16_f32 v86, v2, v6
	v_cvt_pk_bf16_f32 v87, v7, v8
	v_cvt_pk_bf16_f32 v88, v9, v10
	v_cvt_pk_bf16_f32 v89, v11, v12
	global_load_dwordx4 v[102:105], v[176:177], off offset:400
	global_load_dwordx4 v[106:109], v[176:177], off offset:384
	v_mov_b32_e32 v2, v5
	v_mov_b32_e32 v9, v5
	v_mov_b32_e32 v8, v5
	v_mov_b32_e32 v7, v5
	v_mov_b32_e32 v6, v5
	v_mov_b32_e32 v13, v5
	v_mov_b32_e32 v12, v5
	v_mov_b32_e32 v11, v5
	v_mov_b32_e32 v10, v5
	v_mov_b32_e32 v17, v5
	v_mov_b32_e32 v16, v5
	v_mov_b32_e32 v15, v5
	v_mov_b32_e32 v14, v5
	v_mov_b32_e32 v20, v5
	v_mov_b32_e32 v19, v5
	v_mov_b32_e32 v18, v5
	s_waitcnt vmcnt(1)
	v_mul_f32_e32 v102, v95, v102
	s_waitcnt vmcnt(0)
	v_mul_f32_e32 v97, v97, v108
	v_mul_f32_e32 v96, v96, v109
	v_mul_f32_e32 v99, v99, v106
	v_mul_f32_e32 v98, v98, v107
	v_mul_f32_e32 v103, v94, v103
	v_mul_f32_e32 v101, v101, v104
	v_mul_f32_e32 v100, v100, v105
	v_cvt_pk_bf16_f32 v94, v99, v98
	v_cvt_pk_bf16_f32 v95, v97, v96
	v_cvt_pk_bf16_f32 v96, v102, v103
	v_cvt_pk_bf16_f32 v97, v101, v100
	s_cbranch_scc1 .LBB0_280
	s_bfe_u32 s6, s23, 0x40002
	s_lshl_b32 s7, s6, 1
	v_sub_u32_e64 v2, s7, 4 clamp
	s_and_b32 s10, s26, 48
	v_readfirstlane_b32 s8, v2
	v_sub_u32_e64 v2, s7, 3 clamp
	s_min_u32 s3, s8, 24
	v_readfirstlane_b32 s7, v2
	v_sub_u32_e64 v2, s10, 8 clamp
	v_min_u32_e32 v2, 32, v2
	s_mul_i32 s11, s3, 31
	v_add_u32_e32 v2, s11, v2
	v_add_u32_e32 v2, v2, v173
	v_subrev_u32_e32 v2, s10, v2
	s_mul_i32 s6, s6, 62
	v_subrev_u32_e32 v188, s6, v2
	v_sub_u32_e64 v2, s1, 8 clamp
	s_min_u32 s7, s7, 24
	v_min_u32_e32 v4, 32, v2
	v_or_b32_e32 v2, s1, v192
	s_sub_i32 s6, s7, s3
	v_sub_u32_e64 v2, v2, 8 clamp
	s_add_i32 s6, s6, 15
	s_or_b32 s0, s0, s17
	v_min_u32_e32 v5, 48, v2
	v_or_b32_e32 v2, s13, v192
	s_max_i32 s71, s6, 0
	s_mul_i32 s42, s0, 0x1d1
	v_readlane_b32 s52, v252, 12
	v_mul_u32_u24_e32 v2, 0x4800, v2
	s_lshl_b32 s8, s3, 5
	s_lshl_b32 s9, s7, 5
	s_add_i32 s71, s71, 1
	s_lshl_b64 s[0:1], s[42:43], 2
	v_readlane_b32 s64, v252, 24
	v_lshlrev_b32_e32 v2, 1, v2
	v_mov_b32_e32 v3, v195
	v_readlane_b32 s65, v252, 25
	s_add_u32 s0, s64, s0
	v_lshl_add_u64 v[190:191], v[178:179], 0, v[2:3]
	v_add_u32_e32 v2, v4, v170
	v_add_u32_e32 v3, 16, v5
	s_addc_u32 s1, s65, s1
	v_or_b32_e32 v181, s5, v4
	s_lshl_b32 s10, s4, 8
	v_cmp_ge_u32_e32 vcc, v2, v5
	v_cmp_lt_u32_e64 s[4:5], v2, v3
	v_or_b32_e32 v4, 1, v2
	v_readlane_b32 s53, v252, 13
	s_and_b64 s[40:41], vcc, s[4:5]
	v_cmp_ge_u32_e32 vcc, v4, v5
	v_cmp_lt_u32_e64 s[4:5], v4, v3
	v_or_b32_e32 v4, 2, v2
	v_readlane_b32 s54, v252, 14
	v_readlane_b32 s55, v252, 15
	s_and_b64 s[52:53], vcc, s[4:5]
	v_cmp_ge_u32_e32 vcc, v4, v5
	v_cmp_lt_u32_e64 s[4:5], v4, v3
	v_or_b32_e32 v4, 3, v2
	v_readlane_b32 s60, v252, 20
	v_readlane_b32 s61, v252, 21
	s_and_b64 s[54:55], vcc, s[4:5]
	v_cmp_ge_u32_e32 vcc, v4, v5
	v_cmp_lt_u32_e64 s[4:5], v4, v3
	v_or_b32_e32 v4, 4, v2
	v_readlane_b32 s62, v252, 22
	v_readlane_b32 s63, v252, 23
	s_and_b64 s[60:61], vcc, s[4:5]
	v_cmp_ge_u32_e32 vcc, v4, v5
	v_cmp_lt_u32_e64 s[4:5], v4, v3
	v_or_b32_e32 v4, 5, v2
	s_and_b64 s[62:63], vcc, s[4:5]
	v_cmp_ge_u32_e32 vcc, v4, v5
	v_cmp_lt_u32_e64 s[4:5], v4, v3
	v_or_b32_e32 v4, 6, v2
	s_and_b64 s[80:81], vcc, s[4:5]
	v_cmp_ge_u32_e32 vcc, v4, v5
	v_cmp_lt_u32_e64 s[4:5], v4, v3
	v_or_b32_e32 v2, 7, v2
	s_and_b64 s[82:83], vcc, s[4:5]
	v_cmp_ge_u32_e32 vcc, v2, v5
	v_cmp_lt_u32_e64 s[4:5], v2, v3
	s_add_i32 s10, s10, s8
	s_and_b64 s[6:7], vcc, s[4:5]
	s_sub_i32 s4, s10, s9
	v_mov_b32_e32 v175, 0
	s_mov_b32 s70, 0
	s_add_i32 s78, s4, 0x3f00
	v_mov_b32_e32 v253, 0xff800000
	s_movk_i32 s22, 0x1d0
	v_mov_b32_e32 v185, 0xff800000
	v_mov_b32_e32 v203, 0xff800000
	v_mov_b32_e32 v201, 0
	v_mov_b32_e32 v34, 0
	v_mov_b32_e32 v35, v175
	v_mov_b32_e32 v36, v175
	v_mov_b32_e32 v37, v175
	v_mov_b32_e32 v38, 0
	v_mov_b32_e32 v39, v175
	v_mov_b32_e32 v40, v175
	v_mov_b32_e32 v41, v175
	v_mov_b32_e32 v42, 0
	v_mov_b32_e32 v43, v175
	v_mov_b32_e32 v44, v175
	v_mov_b32_e32 v45, v175
	v_mov_b32_e32 v46, 0
	v_mov_b32_e32 v47, v175
	v_mov_b32_e32 v48, v175
	v_mov_b32_e32 v49, v175
	v_mov_b32_e32 v62, 0
	v_mov_b32_e32 v63, v175
	v_mov_b32_e32 v64, v175
	v_mov_b32_e32 v65, v175
	v_mov_b32_e32 v70, 0
	v_mov_b32_e32 v71, v175
	v_mov_b32_e32 v72, v175
	v_mov_b32_e32 v73, v175
	v_mov_b32_e32 v74, 0
	v_mov_b32_e32 v75, v175
	v_mov_b32_e32 v76, v175
	v_mov_b32_e32 v77, v175
	v_mov_b32_e32 v90, 0
	v_mov_b32_e32 v91, v175
	v_mov_b32_e32 v92, v175
	v_mov_b32_e32 v93, v175
	v_mov_b32_e32 v30, 0
	v_mov_b32_e32 v31, v175
	v_mov_b32_e32 v32, v175
	v_mov_b32_e32 v33, v175
	v_mov_b32_e32 v26, 0
	v_mov_b32_e32 v27, v175
	v_mov_b32_e32 v28, v175
	v_mov_b32_e32 v29, v175
	v_mov_b32_e32 v22, 0
	v_mov_b32_e32 v23, v175
	v_mov_b32_e32 v24, v175
	v_mov_b32_e32 v25, v175
	v_mov_b32_e32 v18, 0
	v_mov_b32_e32 v19, v175
	v_mov_b32_e32 v20, v175
	v_mov_b32_e32 v21, v175
	v_mov_b32_e32 v14, 0
	v_mov_b32_e32 v15, v175
	v_mov_b32_e32 v16, v175
	v_mov_b32_e32 v17, v175
	v_mov_b32_e32 v10, 0
	v_mov_b32_e32 v11, v175
	v_mov_b32_e32 v12, v175
	v_mov_b32_e32 v13, v175
	v_mov_b32_e32 v6, 0
	v_mov_b32_e32 v7, v175
	v_mov_b32_e32 v8, v175
	v_mov_b32_e32 v9, v175
	v_mov_b32_e32 v2, 0
	v_mov_b32_e32 v3, v175
	v_mov_b32_e32 v4, v175
	v_mov_b32_e32 v5, v175
	v_readlane_b32 s56, v252, 16
	v_readlane_b32 s57, v252, 17
	v_readlane_b32 s58, v252, 18
	v_readlane_b32 s59, v252, 19
	v_readlane_b32 s66, v252, 26
	v_readlane_b32 s67, v252, 27
	s_barrier
	s_bfe_u32 s27, s23, 0x30003
	s_lshl_b32 s27, s27, 2
	s_sub_i32 s42, s27, 4
	s_max_i32 s42, s42, 0
	s_min_i32 s32, s42, 24
	s_sub_i32 s42, s27, 1
	s_max_i32 s42, s42, 0
	s_min_i32 s42, s42, 24
	s_add_i32 s42, s42, 8
	s_sub_i32 s78, s42, s32
	s_mov_b32 s71, 0
	s_mov_b32 s98, 0
	s_mov_b32 s99, 0
	s_bfe_u32 s27, s12, 0x10001
	s_lshl_b32 s27, s27, 3
	v_lshrrev_b32_e32 v242, 1, v197
	v_sub_u32_e32 v243, v192, v242
	v_and_b32_e32 v243, 3, v243
	v_add_u32_e32 v244, v243, v242
	v_add_u32_e32 v244, s27, v244
	v_and_b32_e32 v244, 15, v244
	v_xor_b32_e32 v245, v192, v244
	v_and_b32_e32 v245, 12, v245
	v_or_b32_e32 v243, v243, v245
	v_lshlrev_b32_e32 v243, 4, v243
	v_lshrrev_b32_e32 v246, 2, v197
	s_lshl_b32 s27, s12, 2
	v_add_u32_e32 v246, s27, v246
	v_mul_u32_u24_e32 v246, 0x6800, v246
	v_add_u32_e32 v229, v246, v243
	v_or_b32_e32 v242, v172, v192
	v_lshrrev_b32_e32 v243, 3, v242
	v_and_b32_e32 v244, 6, v243
	v_and_b32_e32 v245, 7, v242
	v_sub_u32_e32 v245, v245, v244
	v_and_b32_e32 v245, 7, v245
	v_lshlrev_b32_e32 v245, 4, v245
	s_lshl_b32 s27, s12, 3
	v_add_u32_e32 v243, s27, v243
	v_mul_u32_u24_e32 v243, 0x9000, v243
	v_add_u32_e32 v254, v243, v245
	s_mov_b32 s9, 0
	s_sub_i32 s27, s9, s78
	s_lshr_b32 s42, s23, 9
	s_lshl_b32 s101, s42, 2
	s_add_i32 s27, s27, s101
	s_add_i32 s27, s27, 0x100
	s_lshl_b32 s42, s42, 5
	s_add_i32 s42, s42, s32
	s_add_i32 s42, s42, s9
	s_cmp_lt_u32 s9, s78
	s_cselect_b32 s27, s42, s27
	s_lshl_b32 s27, s27, 6
	s_mul_i32 s42, s27, s37
	s_add_u32 s10, s50, s42
	s_addc_u32 s11, s51, 0
	s_lshl_b32 s101, s13, 1
	s_add_i32 s101, s101, 0x2800
	s_add_u32 s10, s10, s101
	s_addc_u32 s11, s11, 0
	s_lshl_b32 s8, s12, 10
	s_add_i32 s8, s8, s98
	s_mov_b32 m0, s8
	s_add_i32 s8, s8, 0x2000
	global_load_lds_dwordx4 v229, s[10:11]
	s_mov_b32 m0, s8
	s_add_u32 s10, s10, 0xd0000
	s_addc_u32 s11, s11, 0
	global_load_lds_dwordx4 v229, s[10:11]
	v_readlane_b32 s10, v252, 55
	v_readlane_b32 s11, v252, 56
	s_mul_i32 s42, s13, 0x9000
	s_lshl_b32 s101, s27, 1
	s_add_i32 s42, s42, s101
	s_add_i32 s8, s8, 0x2000
	s_add_u32 s10, s10, s42
	s_addc_u32 s11, s11, 0
	s_mov_b32 m0, s8
	s_add_i32 s8, s8, 0x2000
	global_load_lds_dwordx4 v254, s[10:11]
	s_mov_b32 m0, s8
	s_add_u32 s10, s10, 0x240000
	s_addc_u32 s11, s11, 0
	global_load_lds_dwordx4 v254, s[10:11]
	s_add_i32 s98, s98, 0x8000
	s_cmp_eq_u32 s98, 0x18000
	s_cselect_b32 s98, 0, s98
	s_mov_b32 s9, 1
	s_sub_i32 s27, s9, s78
	s_lshr_b32 s42, s23, 9
	s_lshl_b32 s101, s42, 2
	s_add_i32 s27, s27, s101
	s_add_i32 s27, s27, 0x100
	s_lshl_b32 s42, s42, 5
	s_add_i32 s42, s42, s32
	s_add_i32 s42, s42, s9
	s_cmp_lt_u32 s9, s78
	s_cselect_b32 s27, s42, s27
	s_lshl_b32 s27, s27, 6
	s_mul_i32 s42, s27, s37
	s_add_u32 s10, s50, s42
	s_addc_u32 s11, s51, 0
	s_lshl_b32 s101, s13, 1
	s_add_i32 s101, s101, 0x2800
	s_add_u32 s10, s10, s101
	s_addc_u32 s11, s11, 0
	s_lshl_b32 s8, s12, 10
	s_add_i32 s8, s8, s98
	s_mov_b32 m0, s8
	s_add_i32 s8, s8, 0x2000
	global_load_lds_dwordx4 v229, s[10:11]
	s_mov_b32 m0, s8
	s_add_u32 s10, s10, 0xd0000
	s_addc_u32 s11, s11, 0
	global_load_lds_dwordx4 v229, s[10:11]
	v_readlane_b32 s10, v252, 55
	v_readlane_b32 s11, v252, 56
	s_mul_i32 s42, s13, 0x9000
	s_lshl_b32 s101, s27, 1
	s_add_i32 s42, s42, s101
	s_add_i32 s8, s8, 0x2000
	s_add_u32 s10, s10, s42
	s_addc_u32 s11, s11, 0
	s_mov_b32 m0, s8
	s_add_i32 s8, s8, 0x2000
	global_load_lds_dwordx4 v254, s[10:11]
	s_mov_b32 m0, s8
	s_add_u32 s10, s10, 0x240000
	s_addc_u32 s11, s11, 0
	global_load_lds_dwordx4 v254, s[10:11]
	s_add_i32 s98, s98, 0x8000
	s_cmp_eq_u32 s98, 0x18000
	s_cselect_b32 s98, 0, s98
	s_and_b32 s27, s23, 3
	s_lshl_b32 s27, s27, 4
	s_sub_i32 s27, s27, 8
	s_max_i32 s27, s27, 0
	s_min_i32 s42, s27, 32
	s_lshr_b32 s101, s42, 3
	v_lshrrev_b32_e32 v242, 2, v192
	v_and_b32_e32 v243, 3, v192
	v_lshl_add_u32 v244, v242, 3, v243
	v_add_u32_e32 v245, s42, v244
	v_add_u32_e32 v246, s101, v242
	v_and_b32_e32 v246, 1, v246
	v_lshl_or_b32 v246, v246, 2, v243
	v_lshrrev_b32_e32 v247, 2, v197
	v_lshl_add_u32 v246, v246, 1, v247
	v_and_b32_e32 v246, 15, v246
	v_lshlrev_b32_e32 v246, 4, v246
	v_lshl_add_u32 v255, v245, 8, v246
	v_and_b32_e32 v246, 1, v242
	v_lshl_or_b32 v246, v246, 2, v243
	v_lshl_add_u32 v246, v246, 1, v247
	v_and_b32_e32 v246, 15, v246
	v_lshlrev_b32_e32 v246, 4, v246
	v_lshl_add_u32 v190, v244, 8, v246
	v_and_b32_e32 v242, 14, v192
	v_add_u32_e32 v242, v242, v247
	v_lshlrev_b32_e32 v243, 7, v192
	v_add_u32_e32 v243, 0x4000, v243
	v_add_u32_e32 v244, s101, v242
	v_and_b32_e32 v244, 7, v244
	v_lshl_add_u32 v191, v244, 4, v243
	v_and_b32_e32 v244, 7, v242
	v_lshl_add_u32 v181, v244, 4, v243
	v_add_u32_e32 v244, 4, v242
	v_and_b32_e32 v244, 7, v244
	v_lshl_add_u32 v249, v244, 4, v243
.Lat_tile_top:
	s_add_i32 s27, s71, 1
	s_add_i32 s42, s78, 4
	s_cmp_lt_u32 s27, s42
	s_cbranch_scc1 .Lat_w4
	s_waitcnt vmcnt(0)
	s_branch .Lat_wdone
.Lat_w4:
	s_waitcnt vmcnt(4)
.Lat_wdone:
	s_barrier
	s_cmp_lt_u32 s71, s78
	s_cbranch_scc0 .Lat_ctx_tile
	s_add_i32 s27, s32, s71
	s_sub_i32 s70, s27, s15
	s_cmp_lt_u32 s70, s2
	s_cselect_b32 s100, 1, 0
	s_cbranch_scc0 .Lat_loc_dma
	v_add_u32_e32 v247, 8, v188
	v_med3_i32 v247, v247, 0, s22
	v_lshlrev_b32_e32 v247, 2, v247
	global_load_dword v213, v247, s[0:1]
	v_add_u32_e32 v248, 9, v188
	v_med3_i32 v248, v248, 0, s22
	v_lshlrev_b32_e32 v248, 2, v248
	global_load_dword v214, v248, s[0:1]
	v_add_u32_e32 v247, 10, v188
	v_med3_i32 v247, v247, 0, s22
	v_lshlrev_b32_e32 v247, 2, v247
	global_load_dword v215, v247, s[0:1]
	v_add_u32_e32 v248, 11, v188
	v_med3_i32 v248, v248, 0, s22
	v_lshlrev_b32_e32 v248, 2, v248
	global_load_dword v216, v248, s[0:1]
	v_add_u32_e32 v247, 12, v188
	v_med3_i32 v247, v247, 0, s22
	v_lshlrev_b32_e32 v247, 2, v247
	global_load_dword v217, v247, s[0:1]
	v_add_u32_e32 v248, 13, v188
	v_med3_i32 v248, v248, 0, s22
	v_lshlrev_b32_e32 v248, 2, v248
	global_load_dword v218, v248, s[0:1]
	v_add_u32_e32 v247, 14, v188
	v_med3_i32 v247, v247, 0, s22
	v_lshlrev_b32_e32 v247, 2, v247
	global_load_dword v219, v247, s[0:1]
	v_add_u32_e32 v248, 15, v188
	v_med3_i32 v248, v248, 0, s22
	v_lshlrev_b32_e32 v248, 2, v248
	global_load_dword v220, v248, s[0:1]
	v_subrev_u32_e32 v247, 23, v188
	v_med3_i32 v247, v247, 0, s22
	v_lshlrev_b32_e32 v247, 2, v247
	global_load_dword v221, v247, s[0:1]
	v_subrev_u32_e32 v248, 22, v188
	v_med3_i32 v248, v248, 0, s22
	v_lshlrev_b32_e32 v248, 2, v248
	global_load_dword v222, v248, s[0:1]
	v_subrev_u32_e32 v247, 21, v188
	v_med3_i32 v247, v247, 0, s22
	v_lshlrev_b32_e32 v247, 2, v247
	global_load_dword v223, v247, s[0:1]
	v_subrev_u32_e32 v248, 20, v188
	v_med3_i32 v248, v248, 0, s22
	v_lshlrev_b32_e32 v248, 2, v248
	global_load_dword v224, v248, s[0:1]
	v_subrev_u32_e32 v247, 19, v188
	v_med3_i32 v247, v247, 0, s22
	v_lshlrev_b32_e32 v247, 2, v247
	global_load_dword v225, v247, s[0:1]
	v_subrev_u32_e32 v248, 18, v188
	v_med3_i32 v248, v248, 0, s22
	v_lshlrev_b32_e32 v248, 2, v248
	global_load_dword v226, v248, s[0:1]
	v_subrev_u32_e32 v247, 17, v188
	v_med3_i32 v247, v247, 0, s22
	v_lshlrev_b32_e32 v247, 2, v247
	global_load_dword v227, v247, s[0:1]
	v_subrev_u32_e32 v248, 16, v188
	v_med3_i32 v248, v248, 0, s22
	v_lshlrev_b32_e32 v248, 2, v248
	global_load_dword v228, v248, s[0:1]
.Lat_loc_dma:
	s_add_i32 s9, s71, 2
	s_sub_i32 s27, s9, s78
	s_lshr_b32 s42, s23, 9
	s_lshl_b32 s101, s42, 2
	s_add_i32 s27, s27, s101
	s_add_i32 s27, s27, 0x100
	s_lshl_b32 s42, s42, 5
	s_add_i32 s42, s42, s32
	s_add_i32 s42, s42, s9
	s_cmp_lt_u32 s9, s78
	s_cselect_b32 s27, s42, s27
	s_lshl_b32 s27, s27, 6
	s_mul_i32 s42, s27, s37
	s_add_u32 s10, s50, s42
	s_addc_u32 s11, s51, 0
	s_lshl_b32 s101, s13, 1
	s_add_i32 s101, s101, 0x2800
	s_add_u32 s10, s10, s101
	s_addc_u32 s11, s11, 0
	s_lshl_b32 s8, s12, 10
	s_add_i32 s8, s8, s98
	s_mov_b32 m0, s8
	s_add_i32 s8, s8, 0x2000
	global_load_lds_dwordx4 v229, s[10:11]
	s_mov_b32 m0, s8
	s_add_u32 s10, s10, 0xd0000
	s_addc_u32 s11, s11, 0
	global_load_lds_dwordx4 v229, s[10:11]
	v_readlane_b32 s10, v252, 55
	v_readlane_b32 s11, v252, 56
	s_mul_i32 s42, s13, 0x9000
	s_lshl_b32 s101, s27, 1
	s_add_i32 s42, s42, s101
	s_add_i32 s8, s8, 0x2000
	s_add_u32 s10, s10, s42
	s_addc_u32 s11, s11, 0
	s_mov_b32 m0, s8
	s_add_i32 s8, s8, 0x2000
	global_load_lds_dwordx4 v254, s[10:11]
	s_mov_b32 m0, s8
	s_add_u32 s10, s10, 0x240000
	s_addc_u32 s11, s11, 0
	global_load_lds_dwordx4 v254, s[10:11]
	s_add_i32 s98, s98, 0x8000
	s_cmp_eq_u32 s98, 0x18000
	s_cselect_b32 s98, 0, s98
	s_cmp_eq_u32 s100, 0
	s_cbranch_scc1 .Lat_tile_next
	v_add_u32_e32 v242, s99, v255
	v_xor_b32_e32 v243, 64, v255
	v_xor_b32_e32 v244, 0x80, v255
	v_xor_b32_e32 v245, 0xc0, v255
	v_add_u32_e32 v243, s99, v243
	v_add_u32_e32 v244, s99, v244
	v_add_u32_e32 v245, s99, v245
	v_add_u32_e32 v246, s99, v191
	ds_read_b128 v[142:145], v242
	ds_read_b128 v[130:133], v243
	ds_read_b128 v[134:137], v244
	ds_read_b128 v[138:141], v245
	ds_read_b128 v[158:161], v242 offset:1024
	ds_read_b128 v[150:153], v243 offset:1024
	ds_read_b128 v[154:157], v244 offset:1024
	ds_read_b128 v[146:149], v245 offset:1024
	ds_read_b128 v[126:129], v246
	ds_read_b128 v[122:125], v246 offset:2048
	ds_read_b128 v[118:121], v246 offset:4096
	ds_read_b128 v[114:117], v246 offset:6144
	ds_read_b128 v[110:113], v246 offset:8192
	ds_read_b128 v[106:109], v246 offset:10240
	ds_read_b128 v[102:105], v246 offset:12288
	ds_read_b128 v[98:101], v246 offset:14336
	s_mov_b32 s100, 2
	s_branch .Lat_body
.Lat_ctx_tile:
	s_add_i32 s9, s71, 2
	s_add_i32 s42, s78, 4
	s_cmp_lt_u32 s9, s42
	s_cbranch_scc0 .Lat_ctx_nodma
	s_sub_i32 s27, s9, s78
	s_lshr_b32 s42, s23, 9
	s_lshl_b32 s101, s42, 2
	s_add_i32 s27, s27, s101
	s_add_i32 s27, s27, 0x100
	s_lshl_b32 s42, s42, 5
	s_add_i32 s42, s42, s32
	s_add_i32 s42, s42, s9
	s_cmp_lt_u32 s9, s78
	s_cselect_b32 s27, s42, s27
	s_lshl_b32 s27, s27, 6
	s_mul_i32 s42, s27, s37
	s_add_u32 s10, s50, s42
	s_addc_u32 s11, s51, 0
	s_lshl_b32 s101, s13, 1
	s_add_i32 s101, s101, 0x2800
	s_add_u32 s10, s10, s101
	s_addc_u32 s11, s11, 0
	s_lshl_b32 s8, s12, 10
	s_add_i32 s8, s8, s98
	s_mov_b32 m0, s8
	s_add_i32 s8, s8, 0x2000
	global_load_lds_dwordx4 v229, s[10:11]
	s_mov_b32 m0, s8
	s_add_u32 s10, s10, 0xd0000
	s_addc_u32 s11, s11, 0
	global_load_lds_dwordx4 v229, s[10:11]
	v_readlane_b32 s10, v252, 55
	v_readlane_b32 s11, v252, 56
	s_mul_i32 s42, s13, 0x9000
	s_lshl_b32 s101, s27, 1
	s_add_i32 s42, s42, s101
	s_add_i32 s8, s8, 0x2000
	s_add_u32 s10, s10, s42
	s_addc_u32 s11, s11, 0
	s_mov_b32 m0, s8
	s_add_i32 s8, s8, 0x2000
	global_load_lds_dwordx4 v254, s[10:11]
	s_mov_b32 m0, s8
	s_add_u32 s10, s10, 0x240000
	s_addc_u32 s11, s11, 0
	global_load_lds_dwordx4 v254, s[10:11]
	s_add_i32 s98, s98, 0x8000
	s_cmp_eq_u32 s98, 0x18000
	s_cselect_b32 s98, 0, s98
.Lat_ctx_nodma:
	s_sub_i32 s27, s71, s78
	s_lshl_b32 s27, s27, 1
	s_add_i32 s70, s2, s27
	v_add_u32_e32 v242, s99, v190
	v_xor_b32_e32 v243, 64, v190
	v_xor_b32_e32 v244, 0x80, v190
	v_xor_b32_e32 v245, 0xc0, v190
	v_add_u32_e32 v243, s99, v243
	v_add_u32_e32 v244, s99, v244
	v_add_u32_e32 v245, s99, v245
	v_add_u32_e32 v246, s99, v181
	ds_read_b128 v[142:145], v242
	ds_read_b128 v[130:133], v243
	ds_read_b128 v[134:137], v244
	ds_read_b128 v[138:141], v245
	ds_read_b128 v[158:161], v242 offset:1024
	ds_read_b128 v[150:153], v243 offset:1024
	ds_read_b128 v[154:157], v244 offset:1024
	ds_read_b128 v[146:149], v245 offset:1024
	ds_read_b128 v[126:129], v246
	ds_read_b128 v[122:125], v246 offset:2048
	ds_read_b128 v[118:121], v246 offset:4096
	ds_read_b128 v[114:117], v246 offset:6144
	ds_read_b128 v[110:113], v246 offset:8192
	ds_read_b128 v[106:109], v246 offset:10240
	ds_read_b128 v[102:105], v246 offset:12288
	ds_read_b128 v[98:101], v246 offset:14336
	s_mov_b32 s100, 0
	s_branch .Lat_body
.Lat_ctx_sub1:
	s_add_i32 s70, s70, 1
	v_add_u32_e32 v242, s99, v190
	v_xor_b32_e32 v243, 64, v190
	v_xor_b32_e32 v244, 0x80, v190
	v_xor_b32_e32 v245, 0xc0, v190
	v_add_u32_e32 v243, s99, v243
	v_add_u32_e32 v244, s99, v244
	v_add_u32_e32 v245, s99, v245
	v_add_u32_e32 v246, s99, v249
	ds_read_b128 v[142:145], v242 offset:8192
	ds_read_b128 v[130:133], v243 offset:8192
	ds_read_b128 v[134:137], v244 offset:8192
	ds_read_b128 v[138:141], v245 offset:8192
	ds_read_b128 v[158:161], v242 offset:9216
	ds_read_b128 v[150:153], v243 offset:9216
	ds_read_b128 v[154:157], v244 offset:9216
	ds_read_b128 v[146:149], v245 offset:9216
	ds_read_b128 v[126:129], v246
	ds_read_b128 v[122:125], v246 offset:2048
	ds_read_b128 v[118:121], v246 offset:4096
	ds_read_b128 v[114:117], v246 offset:6144
	ds_read_b128 v[110:113], v246 offset:8192
	ds_read_b128 v[106:109], v246 offset:10240
	ds_read_b128 v[102:105], v246 offset:12288
	ds_read_b128 v[98:101], v246 offset:14336
	s_mov_b32 s100, 1
.Lat_body:
	s_cmp_ge_i32 s70, s2
	s_cselect_b64 s[8:9], -1, 0
	s_cmp_lt_i32 s70, s2
	s_cselect_b64 s[4:5], -1, 0
	s_cmp_lt_u32 s70, 8
	s_cselect_b64 s[10:11], -1, 0
	s_or_b64 s[10:11], s[8:9], s[10:11]
	v_cndmask_b32_e64 v162, 0, 1, s[4:5]
	s_andn2_b64 vcc, exec, s[10:11]
	v_cmp_ne_u32_e64 s[4:5], 1, v162
	s_cbranch_vccnz .LBB0_309
	s_waitcnt lgkmcnt(8)
	v_mfma_f32_16x16x32_bf16 v[162:165], v[142:145], v[50:53], 0
	s_and_b64 vcc, exec, s[4:5]
	v_mfma_f32_16x16x32_bf16 v[162:165], v[130:133], v[54:57], v[162:165]
	v_mfma_f32_16x16x32_bf16 v[162:165], v[134:137], v[58:61], v[162:165]
	v_mfma_f32_16x16x32_bf16 v[166:169], v[138:141], v[66:69], v[162:165]
	v_mfma_f32_16x16x32_bf16 v[162:165], v[158:161], v[50:53], 0
	v_mfma_f32_16x16x32_bf16 v[162:165], v[150:153], v[54:57], v[162:165]
	v_mfma_f32_16x16x32_bf16 v[162:165], v[154:157], v[58:61], v[162:165]
	v_mfma_f32_16x16x32_bf16 v[162:165], v[146:149], v[66:69], v[162:165]
	s_cbranch_vccnz .LBB0_307
	s_nop 7
	s_waitcnt vmcnt(4)
	v_add_f32_e32 v208, v166, v213
	v_add_f32_e32 v206, v167, v214
	v_add_f32_e32 v209, v168, v215
	v_add_f32_e32 v207, v169, v216
	v_add_f32_e32 v211, v162, v217
	v_add_f32_e32 v210, v163, v218
	v_add_f32_e32 v212, v164, v219
	v_add_f32_e32 v189, v165, v220
	v_cndmask_b32_e64 v208, v253, v208, s[40:41]
	v_cndmask_b32_e64 v206, v253, v206, s[52:53]
	v_cndmask_b32_e64 v209, v253, v209, s[54:55]
	v_cndmask_b32_e64 v207, v253, v207, s[60:61]
	v_cndmask_b32_e64 v211, v253, v211, s[62:63]
	v_cndmask_b32_e64 v210, v253, v210, s[80:81]
	v_cndmask_b32_e64 v212, v253, v212, s[82:83]
	v_cndmask_b32_e64 v189, v253, v189, s[6:7]
	s_branch .LBB0_308

.LBB0_309:
	s_add_i32 s10, s3, s70
	s_cmp_ge_u32 s10, s14
	s_cselect_b64 s[10:11], -1, 0
	s_or_b64 s[8:9], s[8:9], s[10:11]
	s_andn2_b64 vcc, exec, s[8:9]
	s_cbranch_vccnz .LBB0_285
	s_waitcnt lgkmcnt(8)
	v_mfma_f32_16x16x32_bf16 v[142:145], v[142:145], v[78:81], 0
	s_and_b64 vcc, exec, s[4:5]
	v_mfma_f32_16x16x32_bf16 v[130:133], v[130:133], v[82:85], v[142:145]
	v_mfma_f32_16x16x32_bf16 v[130:133], v[134:137], v[86:89], v[130:133]
	v_mfma_f32_16x16x32_bf16 v[134:137], v[138:141], v[94:97], v[130:133]
	v_mfma_f32_16x16x32_bf16 v[130:133], v[158:161], v[78:81], 0
	v_mfma_f32_16x16x32_bf16 v[130:133], v[150:153], v[82:85], v[130:133]
	v_mfma_f32_16x16x32_bf16 v[130:133], v[154:157], v[86:89], v[130:133]
	v_mfma_f32_16x16x32_bf16 v[130:133], v[146:149], v[94:97], v[130:133]
	s_cbranch_vccnz .LBB0_327
	s_nop 7
	s_waitcnt vmcnt(4)
	v_add_f32_e32 v140, v134, v221
	v_add_f32_e32 v138, v135, v222
	v_add_f32_e32 v141, v136, v223
	v_add_f32_e32 v139, v137, v224
	v_add_f32_e32 v143, v130, v225
	v_add_f32_e32 v142, v131, v226
	v_add_f32_e32 v145, v132, v227
	v_add_f32_e32 v144, v133, v228
	v_cndmask_b32_e64 v140, v253, v140, s[40:41]
	v_cndmask_b32_e64 v138, v253, v138, s[52:53]
	v_cndmask_b32_e64 v141, v253, v141, s[54:55]
	v_cndmask_b32_e64 v139, v253, v139, s[60:61]
	v_cndmask_b32_e64 v143, v253, v143, s[62:63]
	v_cndmask_b32_e64 v142, v253, v142, s[80:81]
	v_cndmask_b32_e64 v145, v253, v145, s[82:83]
	v_cndmask_b32_e64 v144, v253, v144, s[6:7]
	s_branch .LBB0_284
.LBB0_327:
	s_nop 6
	v_mov_b32_e32 v144, v133
	v_mov_b32_e32 v145, v132
	v_mov_b32_e32 v142, v131
	v_mov_b32_e32 v143, v130
	v_mov_b32_e32 v139, v137
	v_mov_b32_e32 v141, v136
	v_mov_b32_e32 v138, v135
	v_mov_b32_e32 v140, v134
	s_branch .LBB0_284
.LBB0_284:
	v_max_f32_e32 v130, v138, v138
	v_max_f32_e32 v131, v140, v140
	v_max_f32_e32 v130, v131, v130
	v_max_f32_e32 v131, v139, v139
	v_max_f32_e32 v132, v141, v141
	v_max_f32_e32 v131, v132, v131
	v_max_f32_e32 v132, v144, v144
	v_max_f32_e32 v133, v145, v145
	v_max_f32_e32 v132, v133, v132
	v_max3_f32 v132, v143, v142, v132
	v_max3_f32 v130, v130, v131, v132
	ds_bpermute_b32 v131, v171, v130
	s_waitcnt lgkmcnt(0)
	v_max_f32_e32 v131, v131, v131
	v_max_f32_e32 v130, v130, v131
	ds_bpermute_b32 v131, v199, v130
	s_waitcnt lgkmcnt(0)
	v_max3_f32 v135, v185, v130, v131
	v_sub_f32_e32 v134, v141, v135
	v_mul_f32_e32 v134, 0x3fb8aa3b, v134
	v_exp_f32_e32 v136, v134
	v_sub_f32_e32 v134, v139, v135
	v_mul_f32_e32 v134, 0x3fb8aa3b, v134
	v_sub_f32_e32 v131, v140, v135
	v_exp_f32_e32 v137, v134
	v_sub_f32_e32 v134, v143, v135
	v_mul_f32_e32 v131, 0x3fb8aa3b, v131
	v_sub_f32_e32 v133, v138, v135
	v_mul_f32_e32 v134, 0x3fb8aa3b, v134
	v_exp_f32_e32 v131, v131
	v_mul_f32_e32 v133, 0x3fb8aa3b, v133
	v_exp_f32_e32 v138, v134
	v_sub_f32_e32 v134, v142, v135
	v_exp_f32_e32 v133, v133
	v_mul_f32_e32 v134, 0x3fb8aa3b, v134
	v_exp_f32_e32 v139, v134
	v_sub_f32_e32 v134, v145, v135
	v_mul_f32_e32 v134, 0x3fb8aa3b, v134
	v_sub_f32_e32 v130, v185, v135
	v_add_f32_e32 v132, 0, v131
	v_exp_f32_e32 v140, v134
	v_sub_f32_e32 v134, v144, v135
	v_mul_f32_e32 v130, 0x3fb8aa3b, v130
	v_add_f32_e32 v132, v133, v132
	v_mul_f32_e32 v134, 0x3fb8aa3b, v134
	v_add_f32_e32 v132, v136, v132
	v_exp_f32_e32 v141, v134
	v_exp_f32_e32 v134, v130
	v_add_f32_e32 v132, v137, v132
	v_add_f32_e32 v132, v138, v132
	v_add_f32_e32 v132, v139, v132
	v_add_f32_e32 v132, v140, v132
	v_pk_mul_f32 v[32:33], v[32:33], v[134:135] op_sel_hi:[1,0]
	v_pk_mul_f32 v[30:31], v[30:31], v[134:135] op_sel_hi:[1,0]
	v_pk_mul_f32 v[28:29], v[28:29], v[134:135] op_sel_hi:[1,0]
	v_pk_mul_f32 v[26:27], v[26:27], v[134:135] op_sel_hi:[1,0]
	v_pk_mul_f32 v[24:25], v[24:25], v[134:135] op_sel_hi:[1,0]
	v_pk_mul_f32 v[22:23], v[22:23], v[134:135] op_sel_hi:[1,0]
	v_pk_mul_f32 v[20:21], v[20:21], v[134:135] op_sel_hi:[1,0]
	v_pk_mul_f32 v[18:19], v[18:19], v[134:135] op_sel_hi:[1,0]
	v_pk_mul_f32 v[16:17], v[16:17], v[134:135] op_sel_hi:[1,0]
	v_pk_mul_f32 v[14:15], v[14:15], v[134:135] op_sel_hi:[1,0]
	v_pk_mul_f32 v[12:13], v[12:13], v[134:135] op_sel_hi:[1,0]
	v_pk_mul_f32 v[10:11], v[10:11], v[134:135] op_sel_hi:[1,0]
	v_pk_mul_f32 v[8:9], v[8:9], v[134:135] op_sel_hi:[1,0]
	v_pk_mul_f32 v[6:7], v[6:7], v[134:135] op_sel_hi:[1,0]
	v_pk_mul_f32 v[4:5], v[4:5], v[134:135] op_sel_hi:[1,0]
	v_pk_mul_f32 v[2:3], v[2:3], v[134:135] op_sel_hi:[1,0]
	v_add_f32_e32 v142, v141, v132
	v_cvt_pk_bf16_f32 v130, v131, v133
	v_cvt_pk_bf16_f32 v131, v136, v137
	v_cvt_pk_bf16_f32 v132, v138, v139
	v_cvt_pk_bf16_f32 v133, v140, v141
	v_fmac_f32_e32 v142, v175, v134
	v_mfma_f32_16x16x32_bf16 v[30:33], v[126:129], v[130:133], v[30:33]
	v_mov_b32_e32 v175, v142
	v_mov_b32_e32 v185, v135
	v_mfma_f32_16x16x32_bf16 v[26:29], v[122:125], v[130:133], v[26:29]
	v_mfma_f32_16x16x32_bf16 v[22:25], v[118:121], v[130:133], v[22:25]
	v_mfma_f32_16x16x32_bf16 v[18:21], v[114:117], v[130:133], v[18:21]
	v_mfma_f32_16x16x32_bf16 v[14:17], v[110:113], v[130:133], v[14:17]
	v_mfma_f32_16x16x32_bf16 v[10:13], v[106:109], v[130:133], v[10:13]
	v_mfma_f32_16x16x32_bf16 v[6:9], v[102:105], v[130:133], v[6:9]
	v_mfma_f32_16x16x32_bf16 v[2:5], v[98:101], v[130:133], v[2:5]
.LBB0_285:
	v_add_u32_e32 v188, 31, v188
	s_cmp_eq_u32 s100, 0
	s_cbranch_scc1 .Lat_ctx_sub1
.Lat_tile_next:
	s_add_i32 s99, s99, 0x8000
	s_cmp_eq_u32 s99, 0x18000
	s_cselect_b32 s99, 0, s99
	s_add_i32 s71, s71, 1
	s_add_i32 s27, s78, 4
	s_cmp_lt_u32 s71, s27
	s_cbranch_scc1 .Lat_tile_top
	s_branch .LBB0_279
